# stack9: stack8 + EpiResid and P3 EpiScale epilogue loads hoisted above the barrier
# baseline (speedup 1.0000x reference)
; #define PG8_STAGE(bufoff, gbase, voff) do { _Pragma("unroll") for (int _i = 0; _i < 2; ++_i) \
;         __builtin_amdgcn_global_load_lds((const unsigned*)((const char*)(gbase) + (voff)[_i]), (PG8_LAS unsigned*)(lds + (bufoff) + ldsw + _i * 8192), 16, 0, 0); } while (0)
; #define PG8_LDA(dst, b, h) do { _Pragma("unroll") for (int m = 0; m < 4; ++m) _Pragma("unroll") for (int k = 0; k < 2; ++k) dst[m][k] = *(const PG8_LAS bf16x8*)(lds + PG8_SA(b, h) + aoff + m * 2048 + k * 1024); } while (0)
; #define PG8_LDB(dst, b, h) do { _Pragma("unroll") for (int n = 0; n < 2; ++n) _Pragma("unroll") for (int k = 0; k < 2; ++k) dst[n][k] = *(const PG8_LAS bf16x8*)(lds + PG8_SB(b, h) + boff + n * 2048 + k * 1024); } while (0)
; #define PG8_MMA(ai, bj, At, Bt) do { __builtin_amdgcn_s_setprio(1); _Pragma("unroll") for (int m = 0; m < 4; ++m) _Pragma("unroll") for (int n = 0; n < 2; ++n) _Pragma("unroll") for (int k = 0; k < 2; ++k) \
;         acc[ai][bj][m][n] = __builtin_amdgcn_mfma_f32_16x16x32_bf16(Bt[n][k], At[m][k], acc[ai][bj][m][n], 0, 0, 0); __builtin_amdgcn_s_setprio(0); } while (0)
; #define PG8_WAIT_V(n) asm volatile("s_waitcnt vmcnt(" #n ")" ::: "memory")
; #define PG8_WAIT_L(n) asm volatile("s_waitcnt lgkmcnt(" #n ")" ::: "memory")
; #define PG8_BAR __builtin_amdgcn_s_barrier()
; #define PG8_SCHED __builtin_amdgcn_sched_barrier(0)
; template <class Epi, class Sched, bool ALIGN_EPI = false, bool SP2 = false>
; __device__ __forceinline__ void gemm_phase(PG8_LAS unsigned char* lds, const Gemm g, const Sched& S, const Epi& E) {
;     ...
;             PG8_LDB(B0, 0, 0); PG8_LDB(B1, 0, 1); PG8_SCHED; PG8_LDA(At, 0, 0); PG8_STAGE(PG8_SA(1, 1), a1 + hstep, voffA);
;             PG8_WAIT_V(8); PG8_WAIT_L(0); PG8_BAR; PG8_MMA(0, 0, At, B0); PG8_MMA(0, 1, At, B1); PG8_BAR; PG8_SCHED;
;             PG8_LDA(At, 0, 1); PG8_STAGE(PG8_SB(0, 0), b2, voffB); PG8_STAGE(PG8_SB(0, 1), b2 + hstep, voffB); PG8_STAGE(PG8_SA(0, 0), a2, voffA);
;             PG8_WAIT_V(8); PG8_WAIT_L(0); PG8_BAR; PG8_MMA(1, 0, At, B0); PG8_MMA(1, 1, At, B1); PG8_BAR; PG8_SCHED;
.LBB0_165:
	s_add_u32 s68, s42, 0xfff80080
	s_addc_u32 s69, s43, -1
	s_add_i32 s82, 0, 0x10000
	s_cmp_eq_u32 s71, 28
	s_cselect_b32 s81, s47, s69
	s_cselect_b32 s80, s55, s68
	v_add_u32_e32 v144, s82, v147
	s_cselect_b32 s79, s45, s63
	s_cselect_b32 s78, s58, s59
	s_add_i32 s83, 0, 0x14000
	ds_read_b128 v[140:143], v144
	ds_read_b128 v[156:159], v144 offset:1024
	ds_read_b128 v[160:163], v144 offset:2048
	ds_read_b128 v[164:167], v144 offset:3072
	v_add_u32_e32 v144, s83, v147
	ds_read_b128 v[168:171], v144
	ds_read_b128 v[172:175], v144 offset:1024
	ds_read_b128 v[192:195], v144 offset:2048
	ds_read_b128 v[196:199], v144 offset:3072
	v_lshl_add_u64 v[150:151], s[42:43], 0, v[136:137]
	s_add_i32 m0, s14, 0xc000
	ds_read_b128 v[200:203], v149
	ds_read_b128 v[204:207], v149 offset:1024
	ds_read_b128 v[208:211], v149 offset:2048
	ds_read_b128 v[212:215], v149 offset:3072
	ds_read_b128 v[216:219], v149 offset:4096
	ds_read_b128 v[220:223], v149 offset:5120
	ds_read_b128 v[224:227], v149 offset:6144
	ds_read_b128 v[228:231], v149 offset:7168
	global_load_lds_dwordx4 v[150:151], off
	v_lshl_add_u64 v[150:151], s[42:43], 0, v[138:139]
	s_add_i32 m0, s14, 0xe000
	s_nop 0
	global_load_lds_dwordx4 v[150:151], off
	s_waitcnt vmcnt(8)
	s_waitcnt lgkmcnt(0)
	s_setprio 1
	s_barrier
	v_mfma_f32_16x16x32_bf16 v[124:127], v[140:143], v[200:203], v[124:127]
	v_mfma_f32_16x16x32_bf16 v[120:123], v[160:163], v[200:203], v[120:123]
	v_mfma_f32_16x16x32_bf16 v[108:111], v[140:143], v[208:211], v[108:111]
	v_mfma_f32_16x16x32_bf16 v[104:107], v[160:163], v[208:211], v[104:107]
	v_mfma_f32_16x16x32_bf16 v[92:95], v[140:143], v[216:219], v[92:95]
	v_mfma_f32_16x16x32_bf16 v[88:91], v[160:163], v[216:219], v[88:91]
	v_mfma_f32_16x16x32_bf16 v[76:79], v[140:143], v[224:227], v[76:79]
	v_mfma_f32_16x16x32_bf16 v[72:75], v[160:163], v[224:227], v[72:75]
	v_mfma_f32_16x16x32_bf16 v[124:127], v[156:159], v[204:207], v[124:127]
	v_mfma_f32_16x16x32_bf16 v[120:123], v[164:167], v[204:207], v[120:123]
	v_mfma_f32_16x16x32_bf16 v[108:111], v[156:159], v[212:215], v[108:111]
	v_mfma_f32_16x16x32_bf16 v[104:107], v[164:167], v[212:215], v[104:107]
	v_mfma_f32_16x16x32_bf16 v[92:95], v[156:159], v[220:223], v[92:95]
	v_mfma_f32_16x16x32_bf16 v[88:91], v[164:167], v[220:223], v[88:91]
	v_mfma_f32_16x16x32_bf16 v[76:79], v[156:159], v[228:231], v[76:79]
	v_mfma_f32_16x16x32_bf16 v[72:75], v[164:167], v[228:231], v[72:75]
	v_mfma_f32_16x16x32_bf16 v[116:119], v[168:171], v[200:203], v[116:119]
	v_mfma_f32_16x16x32_bf16 v[112:115], v[192:195], v[200:203], v[112:115]
	v_mfma_f32_16x16x32_bf16 v[100:103], v[168:171], v[208:211], v[100:103]
	v_mfma_f32_16x16x32_bf16 v[96:99], v[192:195], v[208:211], v[96:99]
	v_mfma_f32_16x16x32_bf16 v[84:87], v[168:171], v[216:219], v[84:87]
	v_mfma_f32_16x16x32_bf16 v[80:83], v[192:195], v[216:219], v[80:83]
	v_mfma_f32_16x16x32_bf16 v[68:71], v[168:171], v[224:227], v[68:71]
	v_mfma_f32_16x16x32_bf16 v[64:67], v[192:195], v[224:227], v[64:67]
	v_mfma_f32_16x16x32_bf16 v[116:119], v[172:175], v[204:207], v[116:119]
	v_mfma_f32_16x16x32_bf16 v[112:115], v[196:199], v[204:207], v[112:115]
	v_mfma_f32_16x16x32_bf16 v[100:103], v[172:175], v[212:215], v[100:103]
	v_mfma_f32_16x16x32_bf16 v[96:99], v[196:199], v[212:215], v[96:99]
	v_mfma_f32_16x16x32_bf16 v[84:87], v[172:175], v[220:223], v[84:87]
	v_mfma_f32_16x16x32_bf16 v[80:83], v[196:199], v[220:223], v[80:83]
	v_mfma_f32_16x16x32_bf16 v[68:71], v[172:175], v[228:231], v[68:71]
	v_mfma_f32_16x16x32_bf16 v[64:67], v[196:199], v[228:231], v[64:67]
	s_barrier
	s_setprio 0
	s_add_i32 s68, s82, s0
	v_lshl_add_u64 v[150:151], s[78:79], 0, v[152:153]
	s_mov_b32 m0, s68
	ds_read_b128 v[200:203], v149 offset:16384
	ds_read_b128 v[204:207], v149 offset:17408
	ds_read_b128 v[208:211], v149 offset:18432
	ds_read_b128 v[212:215], v149 offset:19456
	ds_read_b128 v[216:219], v149 offset:20480
	ds_read_b128 v[220:223], v149 offset:21504
	ds_read_b128 v[224:227], v149 offset:22528
	ds_read_b128 v[228:231], v149 offset:23552
	global_load_lds_dwordx4 v[150:151], off
	s_add_i32 m0, s68, 0x2000
	s_add_u32 s68, s78, 0x80000
	v_lshl_add_u64 v[182:183], s[78:79], 0, v[128:129]
	s_addc_u32 s69, s79, 0
	s_add_i32 s82, s83, s0
	global_load_lds_dwordx4 v[182:183], off
	v_lshl_add_u64 v[184:185], s[68:69], 0, v[152:153]
	s_mov_b32 m0, s82
	v_lshl_add_u64 v[188:189], s[80:81], 0, v[130:131]
	global_load_lds_dwordx4 v[184:185], off
	v_lshl_add_u64 v[184:185], s[68:69], 0, v[128:129]
	s_add_i32 m0, s82, 0x2000
	s_nop 0
	global_load_lds_dwordx4 v[184:185], off
	v_lshl_add_u64 v[184:185], s[80:81], 0, v[132:133]
	s_mov_b32 m0, s14
	s_nop 0
	global_load_lds_dwordx4 v[184:185], off
	s_mov_b32 m0, s15
	s_nop 0
	global_load_lds_dwordx4 v[188:189], off
	s_waitcnt vmcnt(8)
	s_waitcnt lgkmcnt(0)
	s_setprio 1
	s_barrier
; #define PG8_STAGE(bufoff, gbase, voff) do { _Pragma("unroll") for (int _i = 0; _i < 2; ++_i) \
;         __builtin_amdgcn_global_load_lds((const unsigned*)((const char*)(gbase) + (voff)[_i]), (PG8_LAS unsigned*)(lds + (bufoff) + ldsw + _i * 8192), 16, 0, 0); } while (0)
; #define PG8_LDA(dst, b, h) do { _Pragma("unroll") for (int m = 0; m < 4; ++m) _Pragma("unroll") for (int k = 0; k < 2; ++k) dst[m][k] = *(const PG8_LAS bf16x8*)(lds + PG8_SA(b, h) + aoff + m * 2048 + k * 1024); } while (0)
; #define PG8_LDB(dst, b, h) do { _Pragma("unroll") for (int n = 0; n < 2; ++n) _Pragma("unroll") for (int k = 0; k < 2; ++k) dst[n][k] = *(const PG8_LAS bf16x8*)(lds + PG8_SB(b, h) + boff + n * 2048 + k * 1024); } while (0)
; #define PG8_MMA(ai, bj, At, Bt) do { __builtin_amdgcn_s_setprio(1); _Pragma("unroll") for (int m = 0; m < 4; ++m) _Pragma("unroll") for (int n = 0; n < 2; ++n) _Pragma("unroll") for (int k = 0; k < 2; ++k) \
;         acc[ai][bj][m][n] = __builtin_amdgcn_mfma_f32_16x16x32_bf16(Bt[n][k], At[m][k], acc[ai][bj][m][n], 0, 0, 0); __builtin_amdgcn_s_setprio(0); } while (0)
; #define PG8_WAIT_V(n) asm volatile("s_waitcnt vmcnt(" #n ")" ::: "memory")
; #define PG8_WAIT_L(n) asm volatile("s_waitcnt lgkmcnt(" #n ")" ::: "memory")
; #define PG8_BAR __builtin_amdgcn_s_barrier()
; #define PG8_SCHED __builtin_amdgcn_sched_barrier(0)
; template <class Epi, class Sched, bool ALIGN_EPI = false, bool SP2 = false>
; __device__ __forceinline__ void gemm_phase(PG8_LAS unsigned char* lds, const Gemm g, const Sched& S, const Epi& E) {
;     ...
;             PG8_WAIT_V(8); PG8_WAIT_L(0); PG8_BAR; PG8_MMA(1, 0, At, B0); PG8_MMA(1, 1, At, B1); PG8_BAR; PG8_SCHED;
;             PG8_LDB(B0, 1, 0); PG8_LDB(B1, 1, 1); PG8_SCHED; PG8_LDA(At, 1, 0); PG8_STAGE(PG8_SA(0, 1), a2 + hstep, voffA);
;             PG8_WAIT_V(8); PG8_WAIT_L(0); PG8_BAR; PG8_MMA(0, 0, At, B0); PG8_MMA(0, 1, At, B1); PG8_BAR; PG8_SCHED;
	v_mfma_f32_16x16x32_bf16 v[60:63], v[140:143], v[200:203], v[60:63]
	v_mfma_f32_16x16x32_bf16 v[56:59], v[160:163], v[200:203], v[56:59]
	v_mfma_f32_16x16x32_bf16 v[44:47], v[140:143], v[208:211], v[44:47]
	v_mfma_f32_16x16x32_bf16 v[40:43], v[160:163], v[208:211], v[40:43]
	v_mfma_f32_16x16x32_bf16 v[28:31], v[140:143], v[216:219], v[28:31]
	v_mfma_f32_16x16x32_bf16 v[24:27], v[160:163], v[216:219], v[24:27]
	v_mfma_f32_16x16x32_bf16 v[12:15], v[140:143], v[224:227], v[12:15]
	v_mfma_f32_16x16x32_bf16 v[8:11], v[160:163], v[224:227], v[8:11]
	v_mfma_f32_16x16x32_bf16 v[60:63], v[156:159], v[204:207], v[60:63]
	v_mfma_f32_16x16x32_bf16 v[56:59], v[164:167], v[204:207], v[56:59]
	v_mfma_f32_16x16x32_bf16 v[44:47], v[156:159], v[212:215], v[44:47]
	v_mfma_f32_16x16x32_bf16 v[40:43], v[164:167], v[212:215], v[40:43]
	v_mfma_f32_16x16x32_bf16 v[28:31], v[156:159], v[220:223], v[28:31]
	v_mfma_f32_16x16x32_bf16 v[24:27], v[164:167], v[220:223], v[24:27]
	v_mfma_f32_16x16x32_bf16 v[12:15], v[156:159], v[228:231], v[12:15]
	v_mfma_f32_16x16x32_bf16 v[8:11], v[164:167], v[228:231], v[8:11]
	v_mfma_f32_16x16x32_bf16 v[52:55], v[168:171], v[200:203], v[52:55]
	v_mfma_f32_16x16x32_bf16 v[48:51], v[192:195], v[200:203], v[48:51]
	v_mfma_f32_16x16x32_bf16 v[36:39], v[168:171], v[208:211], v[36:39]
	v_mfma_f32_16x16x32_bf16 v[32:35], v[192:195], v[208:211], v[32:35]
	v_mfma_f32_16x16x32_bf16 v[20:23], v[168:171], v[216:219], v[20:23]
	v_mfma_f32_16x16x32_bf16 v[16:19], v[192:195], v[216:219], v[16:19]
	v_mfma_f32_16x16x32_bf16 v[4:7], v[168:171], v[224:227], v[4:7]
	v_mfma_f32_16x16x32_bf16 v[0:3], v[192:195], v[224:227], v[0:3]
	v_mfma_f32_16x16x32_bf16 v[52:55], v[172:175], v[204:207], v[52:55]
	v_mfma_f32_16x16x32_bf16 v[48:51], v[196:199], v[204:207], v[48:51]
	v_mfma_f32_16x16x32_bf16 v[36:39], v[172:175], v[212:215], v[36:39]
	v_mfma_f32_16x16x32_bf16 v[32:35], v[196:199], v[212:215], v[32:35]
	v_mfma_f32_16x16x32_bf16 v[20:23], v[172:175], v[220:223], v[20:23]
	v_mfma_f32_16x16x32_bf16 v[16:19], v[196:199], v[220:223], v[16:19]
	v_mfma_f32_16x16x32_bf16 v[4:7], v[172:175], v[228:231], v[4:7]
	v_mfma_f32_16x16x32_bf16 v[0:3], v[196:199], v[228:231], v[0:3]
	s_barrier
	s_setprio 0
	v_add_u32_e32 v144, s93, v147
	s_add_i32 s82, 0, 0x1c000
	ds_read_b128 v[140:143], v144
	ds_read_b128 v[156:159], v144 offset:1024
	ds_read_b128 v[160:163], v144 offset:2048
	ds_read_b128 v[164:167], v144 offset:3072
	v_add_u32_e32 v144, s82, v147
	ds_read_b128 v[168:171], v144
	ds_read_b128 v[172:175], v144 offset:1024
	ds_read_b128 v[192:195], v144 offset:2048
	ds_read_b128 v[196:199], v144 offset:3072
	s_add_u32 s68, s80, 0x80000
	s_addc_u32 s69, s81, 0
	s_mov_b32 m0, s16
	v_lshl_add_u64 v[190:191], s[68:69], 0, v[132:133]
	ds_read_b128 v[200:203], v149 offset:32768
	ds_read_b128 v[204:207], v149 offset:33792
	ds_read_b128 v[208:211], v149 offset:34816
	ds_read_b128 v[212:215], v149 offset:35840
	ds_read_b128 v[216:219], v149 offset:36864
	ds_read_b128 v[220:223], v149 offset:37888
	ds_read_b128 v[224:227], v149 offset:38912
	ds_read_b128 v[228:231], v149 offset:39936
	global_load_lds_dwordx4 v[190:191], off
	v_lshl_add_u64 v[190:191], s[68:69], 0, v[130:131]
	s_mov_b32 m0, s17
	s_nop 0
	global_load_lds_dwordx4 v[190:191], off
	s_waitcnt vmcnt(8)
	s_waitcnt lgkmcnt(0)
	s_setprio 1
	s_barrier
	v_mfma_f32_16x16x32_bf16 v[124:127], v[140:143], v[200:203], v[124:127]
	v_mfma_f32_16x16x32_bf16 v[120:123], v[160:163], v[200:203], v[120:123]
	v_mfma_f32_16x16x32_bf16 v[108:111], v[140:143], v[208:211], v[108:111]
	v_mfma_f32_16x16x32_bf16 v[104:107], v[160:163], v[208:211], v[104:107]
	v_mfma_f32_16x16x32_bf16 v[92:95], v[140:143], v[216:219], v[92:95]
	v_mfma_f32_16x16x32_bf16 v[88:91], v[160:163], v[216:219], v[88:91]
	v_mfma_f32_16x16x32_bf16 v[76:79], v[140:143], v[224:227], v[76:79]
	v_mfma_f32_16x16x32_bf16 v[72:75], v[160:163], v[224:227], v[72:75]
	v_mfma_f32_16x16x32_bf16 v[124:127], v[156:159], v[204:207], v[124:127]
	v_mfma_f32_16x16x32_bf16 v[120:123], v[164:167], v[204:207], v[120:123]
	v_mfma_f32_16x16x32_bf16 v[108:111], v[156:159], v[212:215], v[108:111]
	v_mfma_f32_16x16x32_bf16 v[104:107], v[164:167], v[212:215], v[104:107]
	v_mfma_f32_16x16x32_bf16 v[92:95], v[156:159], v[220:223], v[92:95]
	v_mfma_f32_16x16x32_bf16 v[88:91], v[164:167], v[220:223], v[88:91]
	v_mfma_f32_16x16x32_bf16 v[76:79], v[156:159], v[228:231], v[76:79]
	v_mfma_f32_16x16x32_bf16 v[72:75], v[164:167], v[228:231], v[72:75]
	v_mfma_f32_16x16x32_bf16 v[116:119], v[168:171], v[200:203], v[116:119]
	v_mfma_f32_16x16x32_bf16 v[112:115], v[192:195], v[200:203], v[112:115]
	v_mfma_f32_16x16x32_bf16 v[100:103], v[168:171], v[208:211], v[100:103]
	v_mfma_f32_16x16x32_bf16 v[96:99], v[192:195], v[208:211], v[96:99]
	v_mfma_f32_16x16x32_bf16 v[84:87], v[168:171], v[216:219], v[84:87]
	v_mfma_f32_16x16x32_bf16 v[80:83], v[192:195], v[216:219], v[80:83]
	v_mfma_f32_16x16x32_bf16 v[68:71], v[168:171], v[224:227], v[68:71]
	v_mfma_f32_16x16x32_bf16 v[64:67], v[192:195], v[224:227], v[64:67]
	v_mfma_f32_16x16x32_bf16 v[116:119], v[172:175], v[204:207], v[116:119]
	v_mfma_f32_16x16x32_bf16 v[112:115], v[196:199], v[204:207], v[112:115]
	v_mfma_f32_16x16x32_bf16 v[100:103], v[172:175], v[212:215], v[100:103]
	v_mfma_f32_16x16x32_bf16 v[96:99], v[196:199], v[212:215], v[96:99]
	v_mfma_f32_16x16x32_bf16 v[84:87], v[172:175], v[220:223], v[84:87]
	v_mfma_f32_16x16x32_bf16 v[80:83], v[196:199], v[220:223], v[80:83]
	v_mfma_f32_16x16x32_bf16 v[68:71], v[172:175], v[228:231], v[68:71]
	v_mfma_f32_16x16x32_bf16 v[64:67], v[196:199], v[228:231], v[64:67]
	s_barrier
; #define PG8_STAGE(bufoff, gbase, voff) do { _Pragma("unroll") for (int _i = 0; _i < 2; ++_i) \
;         __builtin_amdgcn_global_load_lds((const unsigned*)((const char*)(gbase) + (voff)[_i]), (PG8_LAS unsigned*)(lds + (bufoff) + ldsw + _i * 8192), 16, 0, 0); } while (0)
; #define PG8_LDA(dst, b, h) do { _Pragma("unroll") for (int m = 0; m < 4; ++m) _Pragma("unroll") for (int k = 0; k < 2; ++k) dst[m][k] = *(const PG8_LAS bf16x8*)(lds + PG8_SA(b, h) + aoff + m * 2048 + k * 1024); } while (0)
; #define PG8_MMA(ai, bj, At, Bt) do { __builtin_amdgcn_s_setprio(1); _Pragma("unroll") for (int m = 0; m < 4; ++m) _Pragma("unroll") for (int n = 0; n < 2; ++n) _Pragma("unroll") for (int k = 0; k < 2; ++k) \
;         acc[ai][bj][m][n] = __builtin_amdgcn_mfma_f32_16x16x32_bf16(Bt[n][k], At[m][k], acc[ai][bj][m][n], 0, 0, 0); __builtin_amdgcn_s_setprio(0); } while (0)
; #define PG8_WAIT_V(n) asm volatile("s_waitcnt vmcnt(" #n ")" ::: "memory")
; #define PG8_WAIT_L(n) asm volatile("s_waitcnt lgkmcnt(" #n ")" ::: "memory")
; #define PG8_BAR __builtin_amdgcn_s_barrier()
; #define PG8_SCHED __builtin_amdgcn_sched_barrier(0)
; __device__ __forceinline__ float row_rs(const float* ssq, int row, int fq) {
;     const f32x4 a = *(const f32x4*)(ssq + (size_t)row * 32 + fq * 8), b = *(const f32x4*)(ssq + (size_t)row * 32 + fq * 8 + 4);
; template <class Epi, class Sched, bool ALIGN_EPI = false, bool SP2 = false>
; __device__ __forceinline__ void gemm_phase(PG8_LAS unsigned char* lds, const Gemm g, const Sched& S, const Epi& E) {
;     ...
;             PG8_LDA(At, 1, 1); PG8_STAGE(PG8_SB(1, 0), b3, voffB); PG8_STAGE(PG8_SB(1, 1), b3 + hstep, voffB); PG8_STAGE(PG8_SA(1, 0), a3, voffA);
;             PG8_WAIT_V(8); PG8_WAIT_L(0); PG8_BAR; PG8_MMA(1, 0, At, B0); PG8_MMA(1, 1, At, B1); PG8_BAR; PG8_SCHED;
	s_setprio 0
	s_add_i32 s68, s93, s0
	v_lshl_add_u64 v[150:151], v[150:151], 0, s[18:19]
	s_mov_b32 m0, s68
	ds_read_b128 v[200:203], v149 offset:49152
	ds_read_b128 v[204:207], v149 offset:50176
	ds_read_b128 v[208:211], v149 offset:51200
	ds_read_b128 v[212:215], v149 offset:52224
	ds_read_b128 v[216:219], v149 offset:53248
	ds_read_b128 v[220:223], v149 offset:54272
	ds_read_b128 v[224:227], v149 offset:55296
	ds_read_b128 v[228:231], v149 offset:56320
	global_load_lds_dwordx4 v[150:151], off
	s_add_i32 m0, s68, 0x2000
	s_add_u32 s68, s78, 0x80080
	v_lshl_add_u64 v[150:151], v[182:183], 0, s[18:19]
	s_addc_u32 s69, s79, 0
	s_add_i32 s78, s82, s0
	global_load_lds_dwordx4 v[150:151], off
	v_lshl_add_u64 v[150:151], s[68:69], 0, v[152:153]
	s_mov_b32 m0, s78
	s_nop 0
	global_load_lds_dwordx4 v[150:151], off
	v_lshl_add_u64 v[150:151], s[68:69], 0, v[128:129]
	s_add_i32 m0, s78, 0x2000
	s_nop 0
	global_load_lds_dwordx4 v[150:151], off
	v_lshl_add_u64 v[150:151], v[184:185], 0, s[18:19]
	s_mov_b32 m0, s22
	s_nop 0
	global_load_lds_dwordx4 v[150:151], off
	v_lshl_add_u64 v[150:151], v[188:189], 0, s[18:19]
	s_mov_b32 m0, s23
	s_nop 0
	global_load_lds_dwordx4 v[150:151], off
	s_waitcnt vmcnt(8)
	s_waitcnt lgkmcnt(0)
	s_setprio 1
	s_barrier
	v_mfma_f32_16x16x32_bf16 v[60:63], v[140:143], v[200:203], v[60:63]
	v_mfma_f32_16x16x32_bf16 v[56:59], v[160:163], v[200:203], v[56:59]
	v_mfma_f32_16x16x32_bf16 v[44:47], v[140:143], v[208:211], v[44:47]
	v_mfma_f32_16x16x32_bf16 v[40:43], v[160:163], v[208:211], v[40:43]
	v_mfma_f32_16x16x32_bf16 v[28:31], v[140:143], v[216:219], v[28:31]
	v_mfma_f32_16x16x32_bf16 v[24:27], v[160:163], v[216:219], v[24:27]
	v_mfma_f32_16x16x32_bf16 v[12:15], v[140:143], v[224:227], v[12:15]
	v_mfma_f32_16x16x32_bf16 v[8:11], v[160:163], v[224:227], v[8:11]
	v_mfma_f32_16x16x32_bf16 v[60:63], v[156:159], v[204:207], v[60:63]
	v_mfma_f32_16x16x32_bf16 v[56:59], v[164:167], v[204:207], v[56:59]
	v_mfma_f32_16x16x32_bf16 v[44:47], v[156:159], v[212:215], v[44:47]
	v_mfma_f32_16x16x32_bf16 v[40:43], v[164:167], v[212:215], v[40:43]
	v_mfma_f32_16x16x32_bf16 v[28:31], v[156:159], v[220:223], v[28:31]
	v_mfma_f32_16x16x32_bf16 v[24:27], v[164:167], v[220:223], v[24:27]
	v_mfma_f32_16x16x32_bf16 v[12:15], v[156:159], v[228:231], v[12:15]
	v_mfma_f32_16x16x32_bf16 v[8:11], v[164:167], v[228:231], v[8:11]
	v_mfma_f32_16x16x32_bf16 v[52:55], v[168:171], v[200:203], v[52:55]
	v_mfma_f32_16x16x32_bf16 v[48:51], v[192:195], v[200:203], v[48:51]
	v_mfma_f32_16x16x32_bf16 v[36:39], v[168:171], v[208:211], v[36:39]
	v_mfma_f32_16x16x32_bf16 v[32:35], v[192:195], v[208:211], v[32:35]
	v_mfma_f32_16x16x32_bf16 v[20:23], v[168:171], v[216:219], v[20:23]
	v_mfma_f32_16x16x32_bf16 v[16:19], v[192:195], v[216:219], v[16:19]
	v_mfma_f32_16x16x32_bf16 v[4:7], v[168:171], v[224:227], v[4:7]
	v_mfma_f32_16x16x32_bf16 v[0:3], v[192:195], v[224:227], v[0:3]
	v_mfma_f32_16x16x32_bf16 v[52:55], v[172:175], v[204:207], v[52:55]
	v_mfma_f32_16x16x32_bf16 v[48:51], v[196:199], v[204:207], v[48:51]
	v_mfma_f32_16x16x32_bf16 v[36:39], v[172:175], v[212:215], v[36:39]
	v_mfma_f32_16x16x32_bf16 v[32:35], v[196:199], v[212:215], v[32:35]
	v_mfma_f32_16x16x32_bf16 v[20:23], v[172:175], v[220:223], v[20:23]
	v_mfma_f32_16x16x32_bf16 v[16:19], v[196:199], v[220:223], v[16:19]
	v_mfma_f32_16x16x32_bf16 v[4:7], v[172:175], v[228:231], v[4:7]
	v_mfma_f32_16x16x32_bf16 v[0:3], v[196:199], v[228:231], v[0:3]
	s_barrier
	s_setprio 0
	s_add_i32 s71, s71, 2
	s_add_u32 s42, s42, 0x100
	s_addc_u32 s43, s43, 0
	s_add_u32 s59, s59, 0x100
	s_addc_u32 s63, s63, 0
	s_cmp_gt_u32 s71, 29
	s_cbranch_scc0 .LBB0_165
	s_andn2_b64 vcc, exec, s[36:37]
	s_cbranch_vccnz .Lp3_pre_skip
	v_lshl_add_u32 v184, s54, 8, v145
	v_cmp_lt_i32_e32 vcc, v179, v180
	v_lshlrev_b32_e32 v184, 7, v184
	v_mov_b32_e32 v185, 0
	v_cndmask_b32_e32 v182, v178, v179, vcc
	v_cmp_lt_i32_e32 vcc, v187, v180
	v_lshl_add_u64 v[184:185], v[184:185], 0, v[134:135]
	v_mov_b32_e32 v154, 0x1000
	v_cndmask_b32_e32 v183, v178, v187, vcc
	v_mov_b32_e32 v155, 0
	v_lshlrev_b32_e32 v182, 2, v182
	v_lshlrev_b32_e32 v183, 2, v183
	global_load_dwordx4 v[164:167], v[184:185], off
	global_load_dwordx4 v[168:171], v[184:185], off offset:16
	global_load_dwordx4 v[172:175], v[184:185], off offset:2048
	global_load_dwordx4 v[188:191], v[184:185], off offset:2064
	v_lshl_add_u64 v[184:185], v[184:185], 0, v[154:155]
	v_mov_b32_e32 v154, 0x3000
	global_load_dwordx4 v[192:195], v[184:185], off
	global_load_dwordx4 v[196:199], v[184:185], off offset:16
	global_load_dwordx4 v[200:203], v[184:185], off offset:2048
	global_load_dwordx4 v[204:207], v[184:185], off offset:2064
	v_lshl_add_u64 v[184:185], v[184:185], 0, v[154:155]
	v_mov_b32_e32 v154, 0x1000
	global_load_dwordx4 v[208:211], v[184:185], off
	global_load_dwordx4 v[212:215], v[184:185], off offset:16
	global_load_dwordx4 v[216:219], v[184:185], off offset:2048
	global_load_dwordx4 v[220:223], v[184:185], off offset:2064
	v_lshl_add_u64 v[184:185], v[184:185], 0, v[154:155]
	global_load_dwordx4 v[224:227], v[184:185], off
	global_load_dwordx4 v[228:231], v[184:185], off offset:16
	global_load_dwordx4 v[232:235], v[184:185], off offset:2048
	global_load_dwordx4 v[248:251], v[184:185], off offset:2064

; #define PG8_STAGE(bufoff, gbase, voff) do { _Pragma("unroll") for (int _i = 0; _i < 2; ++_i) \
;         __builtin_amdgcn_global_load_lds((const unsigned*)((const char*)(gbase) + (voff)[_i]), (PG8_LAS unsigned*)(lds + (bufoff) + ldsw + _i * 8192), 16, 0, 0); } while (0)
; #define PG8_LDA(dst, b, h) do { _Pragma("unroll") for (int m = 0; m < 4; ++m) _Pragma("unroll") for (int k = 0; k < 2; ++k) dst[m][k] = *(const PG8_LAS bf16x8*)(lds + PG8_SA(b, h) + aoff + m * 2048 + k * 1024); } while (0)
; #define PG8_LDB(dst, b, h) do { _Pragma("unroll") for (int n = 0; n < 2; ++n) _Pragma("unroll") for (int k = 0; k < 2; ++k) dst[n][k] = *(const PG8_LAS bf16x8*)(lds + PG8_SB(b, h) + boff + n * 2048 + k * 1024); } while (0)
; #define PG8_MMA(ai, bj, At, Bt) do { __builtin_amdgcn_s_setprio(1); _Pragma("unroll") for (int m = 0; m < 4; ++m) _Pragma("unroll") for (int n = 0; n < 2; ++n) _Pragma("unroll") for (int k = 0; k < 2; ++k) \
;         acc[ai][bj][m][n] = __builtin_amdgcn_mfma_f32_16x16x32_bf16(Bt[n][k], At[m][k], acc[ai][bj][m][n], 0, 0, 0); __builtin_amdgcn_s_setprio(0); } while (0)
; #define PG8_WAIT_V(n) asm volatile("s_waitcnt vmcnt(" #n ")" ::: "memory")
; #define PG8_WAIT_L(n) asm volatile("s_waitcnt lgkmcnt(" #n ")" ::: "memory")
; #define PG8_BAR __builtin_amdgcn_s_barrier()
; #define PG8_SCHED __builtin_amdgcn_sched_barrier(0)
; template <class Epi, class Sched, bool ALIGN_EPI = false, bool SP2 = false>
; __device__ __forceinline__ void gemm_phase(PG8_LAS unsigned char* lds, const Gemm g, const Sched& S, const Epi& E) {
;     ...
;             PG8_LDB(B0, 0, 0); PG8_LDB(B1, 0, 1); PG8_SCHED; PG8_LDA(At, 0, 0); PG8_STAGE(PG8_SA(1, 1), a1 + hstep, voffA);
;             PG8_WAIT_V(8); PG8_WAIT_L(0); PG8_BAR; PG8_MMA(0, 0, At, B0); PG8_MMA(0, 1, At, B1); PG8_BAR; PG8_SCHED;
;             PG8_LDA(At, 0, 1); PG8_STAGE(PG8_SB(0, 0), b2, voffB); PG8_STAGE(PG8_SB(0, 1), b2 + hstep, voffB); PG8_STAGE(PG8_SA(0, 0), a2, voffA);
;             PG8_WAIT_V(8); PG8_WAIT_L(0); PG8_BAR; PG8_MMA(1, 0, At, B0); PG8_MMA(1, 1, At, B1); PG8_BAR; PG8_SCHED;
.LBB0_218:
	s_add_i32 vcc_lo, s46, 2
	s_add_u32 s68, s44, 0x80
	s_addc_u32 s47, s45, 0
	s_add_i32 vcc_hi, 0, 0x10000
	s_cmp_eq_u32 s15, s46
	s_cselect_b32 s47, s83, s47
	s_cselect_b32 s46, s82, s68
	v_add_u32_e32 v146, vcc_hi, v149
	s_cselect_b32 s69, s85, s87
	s_cselect_b32 s68, s84, s86
	s_add_i32 s96, 0, 0x14000
	ds_read_b128 v[138:141], v146
	ds_read_b128 v[142:145], v146 offset:1024
	ds_read_b128 v[156:159], v146 offset:2048
	ds_read_b128 v[160:163], v146 offset:3072
	v_add_u32_e32 v146, s96, v149
	ds_read_b128 v[164:167], v146
	ds_read_b128 v[168:171], v146 offset:1024
	ds_read_b128 v[172:175], v146 offset:2048
	ds_read_b128 v[192:195], v146 offset:3072
	v_lshl_add_u64 v[146:147], s[44:45], 0, v[134:135]
	s_add_i32 m0, s54, 0xc000
	ds_read_b128 v[196:199], v151
	ds_read_b128 v[200:203], v151 offset:1024
	ds_read_b128 v[204:207], v151 offset:2048
	ds_read_b128 v[208:211], v151 offset:3072
	ds_read_b128 v[212:215], v151 offset:4096
	ds_read_b128 v[216:219], v151 offset:5120
	ds_read_b128 v[220:223], v151 offset:6144
	ds_read_b128 v[224:227], v151 offset:7168
	global_load_lds_dwordx4 v[146:147], off
	v_lshl_add_u64 v[146:147], s[44:45], 0, v[136:137]
	s_add_i32 m0, s54, 0xe000
	s_nop 0
	global_load_lds_dwordx4 v[146:147], off
	s_waitcnt vmcnt(8)
	s_waitcnt lgkmcnt(0)
	s_setprio 1
	s_barrier
	v_mfma_f32_16x16x32_bf16 v[124:127], v[138:141], v[196:199], v[124:127]
	v_mfma_f32_16x16x32_bf16 v[120:123], v[156:159], v[196:199], v[120:123]
	v_mfma_f32_16x16x32_bf16 v[108:111], v[138:141], v[204:207], v[108:111]
	v_mfma_f32_16x16x32_bf16 v[104:107], v[156:159], v[204:207], v[104:107]
	v_mfma_f32_16x16x32_bf16 v[92:95], v[138:141], v[212:215], v[92:95]
	v_mfma_f32_16x16x32_bf16 v[88:91], v[156:159], v[212:215], v[88:91]
	v_mfma_f32_16x16x32_bf16 v[76:79], v[138:141], v[220:223], v[76:79]
	v_mfma_f32_16x16x32_bf16 v[72:75], v[156:159], v[220:223], v[72:75]
	v_mfma_f32_16x16x32_bf16 v[124:127], v[142:145], v[200:203], v[124:127]
	v_mfma_f32_16x16x32_bf16 v[120:123], v[160:163], v[200:203], v[120:123]
	v_mfma_f32_16x16x32_bf16 v[108:111], v[142:145], v[208:211], v[108:111]
	v_mfma_f32_16x16x32_bf16 v[104:107], v[160:163], v[208:211], v[104:107]
	v_mfma_f32_16x16x32_bf16 v[92:95], v[142:145], v[216:219], v[92:95]
	v_mfma_f32_16x16x32_bf16 v[88:91], v[160:163], v[216:219], v[88:91]
	v_mfma_f32_16x16x32_bf16 v[76:79], v[142:145], v[224:227], v[76:79]
	v_mfma_f32_16x16x32_bf16 v[72:75], v[160:163], v[224:227], v[72:75]
	v_mfma_f32_16x16x32_bf16 v[116:119], v[164:167], v[196:199], v[116:119]
	v_mfma_f32_16x16x32_bf16 v[112:115], v[172:175], v[196:199], v[112:115]
	v_mfma_f32_16x16x32_bf16 v[100:103], v[164:167], v[204:207], v[100:103]
	v_mfma_f32_16x16x32_bf16 v[96:99], v[172:175], v[204:207], v[96:99]
	v_mfma_f32_16x16x32_bf16 v[84:87], v[164:167], v[212:215], v[84:87]
	v_mfma_f32_16x16x32_bf16 v[80:83], v[172:175], v[212:215], v[80:83]
	v_mfma_f32_16x16x32_bf16 v[68:71], v[164:167], v[220:223], v[68:71]
	v_mfma_f32_16x16x32_bf16 v[64:67], v[172:175], v[220:223], v[64:67]
	v_mfma_f32_16x16x32_bf16 v[116:119], v[168:171], v[200:203], v[116:119]
	v_mfma_f32_16x16x32_bf16 v[112:115], v[192:195], v[200:203], v[112:115]
	v_mfma_f32_16x16x32_bf16 v[100:103], v[168:171], v[208:211], v[100:103]
	v_mfma_f32_16x16x32_bf16 v[96:99], v[192:195], v[208:211], v[96:99]
	v_mfma_f32_16x16x32_bf16 v[84:87], v[168:171], v[216:219], v[84:87]
	v_mfma_f32_16x16x32_bf16 v[80:83], v[192:195], v[216:219], v[80:83]
	v_mfma_f32_16x16x32_bf16 v[68:71], v[168:171], v[224:227], v[68:71]
	v_mfma_f32_16x16x32_bf16 v[64:67], v[192:195], v[224:227], v[64:67]
	s_barrier
	s_setprio 0
	s_add_i32 vcc_hi, vcc_hi, s63
	v_lshl_add_u64 v[146:147], s[68:69], 0, v[152:153]
	s_mov_b32 m0, vcc_hi
	ds_read_b128 v[196:199], v151 offset:16384
	ds_read_b128 v[200:203], v151 offset:17408
	ds_read_b128 v[204:207], v151 offset:18432
	ds_read_b128 v[208:211], v151 offset:19456
	ds_read_b128 v[212:215], v151 offset:20480
	ds_read_b128 v[216:219], v151 offset:21504
	ds_read_b128 v[220:223], v151 offset:22528
	ds_read_b128 v[224:227], v151 offset:23552
	global_load_lds_dwordx4 v[146:147], off
	s_add_i32 m0, vcc_hi, 0x2000
	v_lshl_add_u64 v[182:183], s[68:69], 0, v[128:129]
	s_add_u32 s68, s68, s48
	s_addc_u32 s69, s69, 0
	s_add_i32 s96, s96, s63
	global_load_lds_dwordx4 v[182:183], off
	v_lshl_add_u64 v[184:185], s[68:69], 0, v[152:153]
	s_mov_b32 m0, s96
	v_lshl_add_u64 v[188:189], s[68:69], 0, v[128:129]
	global_load_lds_dwordx4 v[184:185], off
	s_add_i32 m0, s96, 0x2000
	v_lshl_add_u64 v[190:191], s[46:47], 0, v[132:133]
	global_load_lds_dwordx4 v[188:189], off
	s_mov_b32 m0, s54
	v_lshl_add_u64 v[228:229], s[46:47], 0, v[130:131]
	global_load_lds_dwordx4 v[190:191], off
	s_mov_b32 m0, s55
	s_nop 0
	global_load_lds_dwordx4 v[228:229], off
	s_waitcnt vmcnt(8)
	s_waitcnt lgkmcnt(0)
	s_setprio 1
	s_barrier
; #define PG8_STAGE(bufoff, gbase, voff) do { _Pragma("unroll") for (int _i = 0; _i < 2; ++_i) \
;         __builtin_amdgcn_global_load_lds((const unsigned*)((const char*)(gbase) + (voff)[_i]), (PG8_LAS unsigned*)(lds + (bufoff) + ldsw + _i * 8192), 16, 0, 0); } while (0)
; #define PG8_LDA(dst, b, h) do { _Pragma("unroll") for (int m = 0; m < 4; ++m) _Pragma("unroll") for (int k = 0; k < 2; ++k) dst[m][k] = *(const PG8_LAS bf16x8*)(lds + PG8_SA(b, h) + aoff + m * 2048 + k * 1024); } while (0)
; #define PG8_LDB(dst, b, h) do { _Pragma("unroll") for (int n = 0; n < 2; ++n) _Pragma("unroll") for (int k = 0; k < 2; ++k) dst[n][k] = *(const PG8_LAS bf16x8*)(lds + PG8_SB(b, h) + boff + n * 2048 + k * 1024); } while (0)
; #define PG8_MMA(ai, bj, At, Bt) do { __builtin_amdgcn_s_setprio(1); _Pragma("unroll") for (int m = 0; m < 4; ++m) _Pragma("unroll") for (int n = 0; n < 2; ++n) _Pragma("unroll") for (int k = 0; k < 2; ++k) \
;         acc[ai][bj][m][n] = __builtin_amdgcn_mfma_f32_16x16x32_bf16(Bt[n][k], At[m][k], acc[ai][bj][m][n], 0, 0, 0); __builtin_amdgcn_s_setprio(0); } while (0)
; #define PG8_WAIT_V(n) asm volatile("s_waitcnt vmcnt(" #n ")" ::: "memory")
; #define PG8_WAIT_L(n) asm volatile("s_waitcnt lgkmcnt(" #n ")" ::: "memory")
; #define PG8_BAR __builtin_amdgcn_s_barrier()
; #define PG8_SCHED __builtin_amdgcn_sched_barrier(0)
; template <class Epi, class Sched, bool ALIGN_EPI = false, bool SP2 = false>
; __device__ __forceinline__ void gemm_phase(PG8_LAS unsigned char* lds, const Gemm g, const Sched& S, const Epi& E) {
;     ...
;             PG8_WAIT_V(8); PG8_WAIT_L(0); PG8_BAR; PG8_MMA(1, 0, At, B0); PG8_MMA(1, 1, At, B1); PG8_BAR; PG8_SCHED;
;             PG8_LDB(B0, 1, 0); PG8_LDB(B1, 1, 1); PG8_SCHED; PG8_LDA(At, 1, 0); PG8_STAGE(PG8_SA(0, 1), a2 + hstep, voffA);
;             PG8_WAIT_V(8); PG8_WAIT_L(0); PG8_BAR; PG8_MMA(0, 0, At, B0); PG8_MMA(0, 1, At, B1); PG8_BAR; PG8_SCHED;
	v_mfma_f32_16x16x32_bf16 v[60:63], v[138:141], v[196:199], v[60:63]
	v_mfma_f32_16x16x32_bf16 v[56:59], v[156:159], v[196:199], v[56:59]
	v_mfma_f32_16x16x32_bf16 v[44:47], v[138:141], v[204:207], v[44:47]
	v_mfma_f32_16x16x32_bf16 v[40:43], v[156:159], v[204:207], v[40:43]
	v_mfma_f32_16x16x32_bf16 v[28:31], v[138:141], v[212:215], v[28:31]
	v_mfma_f32_16x16x32_bf16 v[24:27], v[156:159], v[212:215], v[24:27]
	v_mfma_f32_16x16x32_bf16 v[12:15], v[138:141], v[220:223], v[12:15]
	v_mfma_f32_16x16x32_bf16 v[8:11], v[156:159], v[220:223], v[8:11]
	v_mfma_f32_16x16x32_bf16 v[60:63], v[142:145], v[200:203], v[60:63]
	v_mfma_f32_16x16x32_bf16 v[56:59], v[160:163], v[200:203], v[56:59]
	v_mfma_f32_16x16x32_bf16 v[44:47], v[142:145], v[208:211], v[44:47]
	v_mfma_f32_16x16x32_bf16 v[40:43], v[160:163], v[208:211], v[40:43]
	v_mfma_f32_16x16x32_bf16 v[28:31], v[142:145], v[216:219], v[28:31]
	v_mfma_f32_16x16x32_bf16 v[24:27], v[160:163], v[216:219], v[24:27]
	v_mfma_f32_16x16x32_bf16 v[12:15], v[142:145], v[224:227], v[12:15]
	v_mfma_f32_16x16x32_bf16 v[8:11], v[160:163], v[224:227], v[8:11]
	v_mfma_f32_16x16x32_bf16 v[52:55], v[164:167], v[196:199], v[52:55]
	v_mfma_f32_16x16x32_bf16 v[48:51], v[172:175], v[196:199], v[48:51]
	v_mfma_f32_16x16x32_bf16 v[36:39], v[164:167], v[204:207], v[36:39]
	v_mfma_f32_16x16x32_bf16 v[32:35], v[172:175], v[204:207], v[32:35]
	v_mfma_f32_16x16x32_bf16 v[20:23], v[164:167], v[212:215], v[20:23]
	v_mfma_f32_16x16x32_bf16 v[16:19], v[172:175], v[212:215], v[16:19]
	v_mfma_f32_16x16x32_bf16 v[4:7], v[164:167], v[220:223], v[4:7]
	v_mfma_f32_16x16x32_bf16 v[0:3], v[172:175], v[220:223], v[0:3]
	v_mfma_f32_16x16x32_bf16 v[52:55], v[168:171], v[200:203], v[52:55]
	v_mfma_f32_16x16x32_bf16 v[48:51], v[192:195], v[200:203], v[48:51]
	v_mfma_f32_16x16x32_bf16 v[36:39], v[168:171], v[208:211], v[36:39]
	v_mfma_f32_16x16x32_bf16 v[32:35], v[192:195], v[208:211], v[32:35]
	v_mfma_f32_16x16x32_bf16 v[20:23], v[168:171], v[216:219], v[20:23]
	v_mfma_f32_16x16x32_bf16 v[16:19], v[192:195], v[216:219], v[16:19]
	v_mfma_f32_16x16x32_bf16 v[4:7], v[168:171], v[224:227], v[4:7]
	v_mfma_f32_16x16x32_bf16 v[0:3], v[192:195], v[224:227], v[0:3]
	s_barrier
	s_setprio 0
	v_add_u32_e32 v155, s93, v149
	s_add_i32 s68, 0, 0x1c000
	ds_read_b128 v[138:141], v155
	ds_read_b128 v[142:145], v155 offset:1024
	ds_read_b128 v[156:159], v155 offset:2048
	ds_read_b128 v[160:163], v155 offset:3072
	v_add_u32_e32 v155, s68, v149
	ds_read_b128 v[164:167], v155
	ds_read_b128 v[168:171], v155 offset:1024
	ds_read_b128 v[172:175], v155 offset:2048
	ds_read_b128 v[192:195], v155 offset:3072
	s_add_u32 s46, s46, s48
	s_addc_u32 s47, s47, 0
	s_mov_b32 m0, s34
	v_lshl_add_u64 v[230:231], s[46:47], 0, v[132:133]
	ds_read_b128 v[196:199], v151 offset:32768
	ds_read_b128 v[200:203], v151 offset:33792
	ds_read_b128 v[204:207], v151 offset:34816
	ds_read_b128 v[208:211], v151 offset:35840
	ds_read_b128 v[212:215], v151 offset:36864
	ds_read_b128 v[216:219], v151 offset:37888
	ds_read_b128 v[220:223], v151 offset:38912
	ds_read_b128 v[224:227], v151 offset:39936
	global_load_lds_dwordx4 v[230:231], off
	v_lshl_add_u64 v[230:231], s[46:47], 0, v[130:131]
	s_mov_b32 m0, s95
	s_nop 0
	global_load_lds_dwordx4 v[230:231], off
	s_waitcnt vmcnt(8)
	s_waitcnt lgkmcnt(0)
	s_setprio 1
	s_barrier
	v_mfma_f32_16x16x32_bf16 v[124:127], v[138:141], v[196:199], v[124:127]
	v_mfma_f32_16x16x32_bf16 v[120:123], v[156:159], v[196:199], v[120:123]
	v_mfma_f32_16x16x32_bf16 v[108:111], v[138:141], v[204:207], v[108:111]
	v_mfma_f32_16x16x32_bf16 v[104:107], v[156:159], v[204:207], v[104:107]
	v_mfma_f32_16x16x32_bf16 v[92:95], v[138:141], v[212:215], v[92:95]
	v_mfma_f32_16x16x32_bf16 v[88:91], v[156:159], v[212:215], v[88:91]
	v_mfma_f32_16x16x32_bf16 v[76:79], v[138:141], v[220:223], v[76:79]
	v_mfma_f32_16x16x32_bf16 v[72:75], v[156:159], v[220:223], v[72:75]
	v_mfma_f32_16x16x32_bf16 v[124:127], v[142:145], v[200:203], v[124:127]
	v_mfma_f32_16x16x32_bf16 v[120:123], v[160:163], v[200:203], v[120:123]
	v_mfma_f32_16x16x32_bf16 v[108:111], v[142:145], v[208:211], v[108:111]
	v_mfma_f32_16x16x32_bf16 v[104:107], v[160:163], v[208:211], v[104:107]
	v_mfma_f32_16x16x32_bf16 v[92:95], v[142:145], v[216:219], v[92:95]
	v_mfma_f32_16x16x32_bf16 v[88:91], v[160:163], v[216:219], v[88:91]
	v_mfma_f32_16x16x32_bf16 v[76:79], v[142:145], v[224:227], v[76:79]
	v_mfma_f32_16x16x32_bf16 v[72:75], v[160:163], v[224:227], v[72:75]
	v_mfma_f32_16x16x32_bf16 v[116:119], v[164:167], v[196:199], v[116:119]
	v_mfma_f32_16x16x32_bf16 v[112:115], v[172:175], v[196:199], v[112:115]
	v_mfma_f32_16x16x32_bf16 v[100:103], v[164:167], v[204:207], v[100:103]
	v_mfma_f32_16x16x32_bf16 v[96:99], v[172:175], v[204:207], v[96:99]
	v_mfma_f32_16x16x32_bf16 v[84:87], v[164:167], v[212:215], v[84:87]
	v_mfma_f32_16x16x32_bf16 v[80:83], v[172:175], v[212:215], v[80:83]
	v_mfma_f32_16x16x32_bf16 v[68:71], v[164:167], v[220:223], v[68:71]
	v_mfma_f32_16x16x32_bf16 v[64:67], v[172:175], v[220:223], v[64:67]
	v_mfma_f32_16x16x32_bf16 v[116:119], v[168:171], v[200:203], v[116:119]
	v_mfma_f32_16x16x32_bf16 v[112:115], v[192:195], v[200:203], v[112:115]
	v_mfma_f32_16x16x32_bf16 v[100:103], v[168:171], v[208:211], v[100:103]
	v_mfma_f32_16x16x32_bf16 v[96:99], v[192:195], v[208:211], v[96:99]
	v_mfma_f32_16x16x32_bf16 v[84:87], v[168:171], v[216:219], v[84:87]
	v_mfma_f32_16x16x32_bf16 v[80:83], v[192:195], v[216:219], v[80:83]
	v_mfma_f32_16x16x32_bf16 v[68:71], v[168:171], v[224:227], v[68:71]
	v_mfma_f32_16x16x32_bf16 v[64:67], v[192:195], v[224:227], v[64:67]
	s_barrier
; #define PG8_STAGE(bufoff, gbase, voff) do { _Pragma("unroll") for (int _i = 0; _i < 2; ++_i) \
;         __builtin_amdgcn_global_load_lds((const unsigned*)((const char*)(gbase) + (voff)[_i]), (PG8_LAS unsigned*)(lds + (bufoff) + ldsw + _i * 8192), 16, 0, 0); } while (0)
; #define PG8_LDA(dst, b, h) do { _Pragma("unroll") for (int m = 0; m < 4; ++m) _Pragma("unroll") for (int k = 0; k < 2; ++k) dst[m][k] = *(const PG8_LAS bf16x8*)(lds + PG8_SA(b, h) + aoff + m * 2048 + k * 1024); } while (0)
; #define PG8_MMA(ai, bj, At, Bt) do { __builtin_amdgcn_s_setprio(1); _Pragma("unroll") for (int m = 0; m < 4; ++m) _Pragma("unroll") for (int n = 0; n < 2; ++n) _Pragma("unroll") for (int k = 0; k < 2; ++k) \
;         acc[ai][bj][m][n] = __builtin_amdgcn_mfma_f32_16x16x32_bf16(Bt[n][k], At[m][k], acc[ai][bj][m][n], 0, 0, 0); __builtin_amdgcn_s_setprio(0); } while (0)
; #define PG8_WAIT_V(n) asm volatile("s_waitcnt vmcnt(" #n ")" ::: "memory")
; #define PG8_WAIT_L(n) asm volatile("s_waitcnt lgkmcnt(" #n ")" ::: "memory")
; #define PG8_BAR __builtin_amdgcn_s_barrier()
; #define PG8_SCHED __builtin_amdgcn_sched_barrier(0)
;     __device__ __forceinline__ void operator()(const f32x4 (&acc)[2][2][4][2], const Unit& u, int wr, int wc, int fr, int fq) const {
;     ...
;                 for (int bj = 0; bj < 2; ++bj) { const size_t off = (size_t)row * 2048 + col0 + bj * HALF;
;                     f32x4 b0, b1;
;                     if (base32) { b0 = *(const f32x4*)(base32 + off); b1 = *(const f32x4*)(base32 + off + 4); }
;                     else { const u32x4 bw = *(const u32x4*)(xb + off);
; template <class Epi, class Sched, bool ALIGN_EPI = false, bool SP2 = false>
; __device__ __forceinline__ void gemm_phase(PG8_LAS unsigned char* lds, const Gemm g, const Sched& S, const Epi& E) {
;     ...
;             PG8_LDA(At, 1, 1); PG8_STAGE(PG8_SB(1, 0), b3, voffB); PG8_STAGE(PG8_SB(1, 1), b3 + hstep, voffB); PG8_STAGE(PG8_SA(1, 0), a3, voffA);
;             PG8_WAIT_V(8); PG8_WAIT_L(0); PG8_BAR; PG8_MMA(1, 0, At, B0); PG8_MMA(1, 1, At, B1); PG8_BAR; PG8_SCHED;
	s_setprio 0
	s_add_i32 s46, s93, s63
	v_lshl_add_u64 v[146:147], v[146:147], 0, s[18:19]
	s_mov_b32 m0, s46
	ds_read_b128 v[196:199], v151 offset:49152
	ds_read_b128 v[200:203], v151 offset:50176
	ds_read_b128 v[204:207], v151 offset:51200
	ds_read_b128 v[208:211], v151 offset:52224
	ds_read_b128 v[212:215], v151 offset:53248
	ds_read_b128 v[216:219], v151 offset:54272
	ds_read_b128 v[220:223], v151 offset:55296
	ds_read_b128 v[224:227], v151 offset:56320
	global_load_lds_dwordx4 v[146:147], off
	v_lshl_add_u64 v[146:147], v[182:183], 0, s[18:19]
	s_add_i32 m0, s46, 0x2000
	s_add_i32 s46, s68, s63
	global_load_lds_dwordx4 v[146:147], off
	v_lshl_add_u64 v[146:147], v[184:185], 0, s[18:19]
	s_mov_b32 m0, s46
	s_nop 0
	global_load_lds_dwordx4 v[146:147], off
	v_lshl_add_u64 v[146:147], v[188:189], 0, s[18:19]
	s_add_i32 m0, s46, 0x2000
	s_nop 0
	global_load_lds_dwordx4 v[146:147], off
	v_lshl_add_u64 v[146:147], v[190:191], 0, s[18:19]
	s_mov_b32 m0, s0
	s_nop 0
	global_load_lds_dwordx4 v[146:147], off
	v_lshl_add_u64 v[146:147], v[228:229], 0, s[18:19]
	s_mov_b32 m0, s58
	s_nop 0
	global_load_lds_dwordx4 v[146:147], off
	s_waitcnt vmcnt(8)
	s_waitcnt lgkmcnt(0)
	s_setprio 1
	s_barrier
	v_mfma_f32_16x16x32_bf16 v[60:63], v[138:141], v[196:199], v[60:63]
	v_mfma_f32_16x16x32_bf16 v[56:59], v[156:159], v[196:199], v[56:59]
	v_mfma_f32_16x16x32_bf16 v[44:47], v[138:141], v[204:207], v[44:47]
	v_mfma_f32_16x16x32_bf16 v[40:43], v[156:159], v[204:207], v[40:43]
	v_mfma_f32_16x16x32_bf16 v[28:31], v[138:141], v[212:215], v[28:31]
	v_mfma_f32_16x16x32_bf16 v[24:27], v[156:159], v[212:215], v[24:27]
	v_mfma_f32_16x16x32_bf16 v[12:15], v[138:141], v[220:223], v[12:15]
	v_mfma_f32_16x16x32_bf16 v[8:11], v[156:159], v[220:223], v[8:11]
	v_mfma_f32_16x16x32_bf16 v[60:63], v[142:145], v[200:203], v[60:63]
	v_mfma_f32_16x16x32_bf16 v[56:59], v[160:163], v[200:203], v[56:59]
	v_mfma_f32_16x16x32_bf16 v[44:47], v[142:145], v[208:211], v[44:47]
	v_mfma_f32_16x16x32_bf16 v[40:43], v[160:163], v[208:211], v[40:43]
	v_mfma_f32_16x16x32_bf16 v[28:31], v[142:145], v[216:219], v[28:31]
	v_mfma_f32_16x16x32_bf16 v[24:27], v[160:163], v[216:219], v[24:27]
	v_mfma_f32_16x16x32_bf16 v[12:15], v[142:145], v[224:227], v[12:15]
	v_mfma_f32_16x16x32_bf16 v[8:11], v[160:163], v[224:227], v[8:11]
	v_mfma_f32_16x16x32_bf16 v[52:55], v[164:167], v[196:199], v[52:55]
	v_mfma_f32_16x16x32_bf16 v[48:51], v[172:175], v[196:199], v[48:51]
	v_mfma_f32_16x16x32_bf16 v[36:39], v[164:167], v[204:207], v[36:39]
	v_mfma_f32_16x16x32_bf16 v[32:35], v[172:175], v[204:207], v[32:35]
	v_mfma_f32_16x16x32_bf16 v[20:23], v[164:167], v[212:215], v[20:23]
	v_mfma_f32_16x16x32_bf16 v[16:19], v[172:175], v[212:215], v[16:19]
	v_mfma_f32_16x16x32_bf16 v[4:7], v[164:167], v[220:223], v[4:7]
	v_mfma_f32_16x16x32_bf16 v[0:3], v[172:175], v[220:223], v[0:3]
	v_mfma_f32_16x16x32_bf16 v[52:55], v[168:171], v[200:203], v[52:55]
	v_mfma_f32_16x16x32_bf16 v[48:51], v[192:195], v[200:203], v[48:51]
	v_mfma_f32_16x16x32_bf16 v[36:39], v[168:171], v[208:211], v[36:39]
	v_mfma_f32_16x16x32_bf16 v[32:35], v[192:195], v[208:211], v[32:35]
	v_mfma_f32_16x16x32_bf16 v[20:23], v[168:171], v[216:219], v[20:23]
	v_mfma_f32_16x16x32_bf16 v[16:19], v[192:195], v[216:219], v[16:19]
	v_mfma_f32_16x16x32_bf16 v[4:7], v[168:171], v[224:227], v[4:7]
	v_mfma_f32_16x16x32_bf16 v[0:3], v[192:195], v[224:227], v[0:3]
	s_barrier
	s_setprio 0
	s_add_u32 s44, s44, 0x100
	s_addc_u32 s45, s45, 0
	s_add_u32 s86, s86, 0x100
	s_addc_u32 s87, s87, 0
	s_cmp_ge_u32 vcc_lo, s14
	s_mov_b32 s46, vcc_lo
	s_cbranch_scc0 .LBB0_218
	v_lshl_add_u32 v188, s26, 8, v148
	v_lshl_or_b32 v190, s17, 8, v150
	v_mov_b32_e32 v189, 0
	v_mov_b32_e32 v191, 0
	v_lshlrev_b64 v[182:183], 11, v[188:189]
	v_mov_b32_e32 v184, 0x10000
	v_lshl_add_u64 v[182:183], v[182:183], 0, v[190:191]
	v_mov_b32_e32 v185, 0
	v_lshl_add_u64 v[182:183], v[182:183], 1, s[12:13]
	global_load_dwordx4 v[164:167], v[182:183], off
	global_load_dwordx4 v[168:171], v[182:183], off offset:256
	v_lshl_add_u64 v[182:183], v[182:183], 0, v[184:185]
	global_load_dwordx4 v[172:175], v[182:183], off
	global_load_dwordx4 v[192:195], v[182:183], off offset:256
	v_lshl_add_u64 v[182:183], v[182:183], 0, v[184:185]
	global_load_dwordx4 v[196:199], v[182:183], off
	global_load_dwordx4 v[200:203], v[182:183], off offset:256
	v_lshl_add_u64 v[182:183], v[182:183], 0, v[184:185]
	global_load_dwordx4 v[204:207], v[182:183], off
	global_load_dwordx4 v[208:211], v[182:183], off offset:256
	v_mov_b32_e32 v184, 0x50000
	s_nop 0
	v_lshl_add_u64 v[182:183], v[182:183], 0, v[184:185]
	v_mov_b32_e32 v184, 0x10000
	global_load_dwordx4 v[212:215], v[182:183], off
	global_load_dwordx4 v[216:219], v[182:183], off offset:256
	v_lshl_add_u64 v[182:183], v[182:183], 0, v[184:185]
	global_load_dwordx4 v[220:223], v[182:183], off
	global_load_dwordx4 v[224:227], v[182:183], off offset:256
	v_lshl_add_u64 v[182:183], v[182:183], 0, v[184:185]
	global_load_dwordx4 v[228:231], v[182:183], off
	global_load_dwordx4 v[232:235], v[182:183], off offset:256
	v_lshl_add_u64 v[182:183], v[182:183], 0, v[184:185]
	global_load_dwordx4 v[240:243], v[182:183], off
	global_load_dwordx4 v[244:247], v[182:183], off offset:256
	s_and_b64 vcc, exec, s[36:37]
	s_cbranch_vccz .LBB0_221
	s_barrier
